# speedup vs baseline: 1.0461x; 1.0008x over previous
; #define STAGE_A(Poff, off, hrow) do { const unsigned _s = (off) + (unsigned)(hrow) * lda2;                                \
;     GLDS(ldsw + (Poff), offA, srdA, _s); GLDS(ldsw + (Poff) + 8192, offA, srdA, _s + lda128); } while (0)
; #define STAGE_B(Poff, off, hrow) do { const unsigned _s = (off) + (unsigned)(hrow) * ldb2;                                \
;     GLDS(ldsw + (Poff), offB, srdB, _s); GLDS(ldsw + (Poff) + 8192, offB, srdB, _s + ldb128); } while (0)
; #define LDA(dst, b, h) _Pragma("unroll") for (int m = 0; m < 4; ++m) _Pragma("unroll") for (int k = 0; k < 2; ++k) \
;     dst[m][k] = *reinterpret_cast<const bf16x8*>((const char*)SA(b, h) + aoff + (m * 2 + k) * 1024)
; #define LDB(dst, b, h) _Pragma("unroll") for (int n = 0; n < 2; ++n) _Pragma("unroll") for (int k = 0; k < 2; ++k) \
;     dst[n][k] = *reinterpret_cast<const bf16x8*>((const char*)SB(b, h) + boff + (n * 2 + k) * 1024)
; #define WAIT_V(n) asm volatile("s_waitcnt vmcnt(" #n ")" ::: "memory")
; #define WAIT_L(n) asm volatile("s_waitcnt lgkmcnt(" #n ")" ::: "memory")
; #define BAR __builtin_amdgcn_s_barrier()
; #define SCHED __builtin_amdgcn_sched_barrier(0)
; __device__ __forceinline__ void gemm_phase(const int tid_, const GemmArgs& ga, u16* shm) {
;     ...
;       for (int t = 0; t < nt; t += 2) {
;         const bool last = t + 2 >= nt;
;         const unsigned pA1 = gA + (unsigned)(t + 1) * 128u;
;         const unsigned pA2 = last ? gAn : gA + (unsigned)(t + 2) * 128u;
;         const unsigned pB2 = last ? gBn : gB + (unsigned)(t + 2) * 128u;
;         LDB(B0, 0, 0); SCHED; LDA(At, 0, 0); STAGE_A(SAO(1, 1), pA1, HALF);
;         WAIT_L(8); BAR; WAIT_L(0); MMA(0, 0, At, B0); BAR; SCHED;
;         LDB(B1, 0, 1); STAGE_B(SBO(0, 0), pB2, 0);
;         BAR; WAIT_L(0); MMA(0, 1, At, B1); BAR;
;         LDA(At, 0, 1); STAGE_A(SAO(0, 0), pA2, 0);
;         BAR; WAIT_L(0); MMA(1, 0, At, B0); BAR; SCHED;
;         STAGE_B(SBO(0, 1), pB2, HALF);
;         WAIT_V(6); BAR; MMA(1, 1, At, B1); BAR;
.LBB0_316:
	v_add_u32_e32 v96, 0x10000, v224
	s_mov_b32 s6, s78
	ds_read_b128 v[132:135], v96
	ds_read_b128 v[136:139], v96 offset:1024
	ds_read_b128 v[140:143], v96 offset:2048
	ds_read_b128 v[144:147], v96 offset:3072
	s_add_i32 s78, s78, 2
	s_lshl_b32 s6, s6, 7
	s_lshl_b32 s7, s78, 7
	s_add_i32 s10, s79, s6
	s_add_i32 s8, s7, s54
	s_add_i32 s9, s7, s1
	s_add_i32 s11, s10, s62
	s_cmp_ge_u32 s78, s67
	s_cselect_b64 s[28:29], -1, 0
	s_and_b64 s[6:7], s[28:29], exec
	s_cselect_b32 s6, s19, s8
	ds_read_b128 v[152:155], v225
	ds_read_b128 v[156:159], v225 offset:1024
	ds_read_b128 v[160:163], v225 offset:2048
	ds_read_b128 v[164:167], v225 offset:3072
	ds_read_b128 v[168:171], v225 offset:4096
	ds_read_b128 v[172:175], v225 offset:5120
	ds_read_b128 v[176:179], v225 offset:6144
	s_mov_b32 m0, s66
	ds_read_b128 v[180:183], v225 offset:7168
	buffer_load_dwordx4 v222, s[48:51], s10 offen lds
	s_mov_b32 m0, s18
	s_nop 0
	buffer_load_dwordx4 v222, s[48:51], s11 offen lds
	v_add_u32_e32 v96, 0x14000, v224
	ds_read_b128 v[184:187], v96
	ds_read_b128 v[188:191], v96 offset:1024
	ds_read_b128 v[192:195], v96 offset:2048
	ds_read_b128 v[196:199], v96 offset:3072
	s_waitcnt lgkmcnt(0)
	s_waitcnt vmcnt(8)
	s_barrier
	v_mfma_f32_16x16x32_bf16 v[128:131], v[132:135], v[152:155], v[128:131]
	v_mfma_f32_16x16x32_bf16 v[124:127], v[140:143], v[152:155], v[124:127]
	v_mfma_f32_16x16x32_bf16 v[120:123], v[132:135], v[160:163], v[120:123]
	v_mfma_f32_16x16x32_bf16 v[116:119], v[140:143], v[160:163], v[116:119]
	v_mfma_f32_16x16x32_bf16 v[112:115], v[132:135], v[168:171], v[112:115]
	v_mfma_f32_16x16x32_bf16 v[108:111], v[140:143], v[168:171], v[108:111]
	v_mfma_f32_16x16x32_bf16 v[104:107], v[132:135], v[176:179], v[104:107]
	v_mfma_f32_16x16x32_bf16 v[98:101], v[140:143], v[176:179], v[100:103]
	v_mfma_f32_16x16x32_bf16 v[128:131], v[136:139], v[156:159], v[128:131]
	v_mfma_f32_16x16x32_bf16 v[124:127], v[144:147], v[156:159], v[124:127]
	v_mfma_f32_16x16x32_bf16 v[120:123], v[136:139], v[164:167], v[120:123]
	v_mfma_f32_16x16x32_bf16 v[116:119], v[144:147], v[164:167], v[116:119]
	v_mfma_f32_16x16x32_bf16 v[112:115], v[136:139], v[172:175], v[112:115]
	v_mfma_f32_16x16x32_bf16 v[108:111], v[144:147], v[172:175], v[108:111]
	v_mfma_f32_16x16x32_bf16 v[102:105], v[136:139], v[180:183], v[104:107]
	v_mfma_f32_16x16x32_bf16 v[98:101], v[144:147], v[180:183], v[98:101]
	v_mfma_f32_16x16x32_bf16 v[92:95], v[184:187], v[152:155], v[92:95]
	v_mfma_f32_16x16x32_bf16 v[88:91], v[192:195], v[152:155], v[88:91]
	v_mfma_f32_16x16x32_bf16 v[84:87], v[184:187], v[160:163], v[84:87]
	v_mfma_f32_16x16x32_bf16 v[80:83], v[192:195], v[160:163], v[80:83]
	v_mfma_f32_16x16x32_bf16 v[76:79], v[184:187], v[168:171], v[76:79]
	v_mfma_f32_16x16x32_bf16 v[72:75], v[192:195], v[168:171], v[72:75]
	v_mfma_f32_16x16x32_bf16 v[68:71], v[184:187], v[176:179], v[68:71]
	v_mfma_f32_16x16x32_bf16 v[64:67], v[192:195], v[176:179], v[64:67]
	v_mfma_f32_16x16x32_bf16 v[92:95], v[188:191], v[156:159], v[92:95]
	v_mfma_f32_16x16x32_bf16 v[88:91], v[196:199], v[156:159], v[88:91]
	v_mfma_f32_16x16x32_bf16 v[84:87], v[188:191], v[164:167], v[84:87]
	v_mfma_f32_16x16x32_bf16 v[80:83], v[196:199], v[164:167], v[80:83]
	v_mfma_f32_16x16x32_bf16 v[76:79], v[188:191], v[172:175], v[76:79]
	v_mfma_f32_16x16x32_bf16 v[72:75], v[196:199], v[172:175], v[72:75]
	v_mfma_f32_16x16x32_bf16 v[68:71], v[188:191], v[180:183], v[68:71]
	v_mfma_f32_16x16x32_bf16 v[64:67], v[196:199], v[180:183], v[64:67]
	s_barrier
	ds_read_b128 v[152:155], v225 offset:16384
	ds_read_b128 v[156:159], v225 offset:17408
	ds_read_b128 v[160:163], v225 offset:18432
	ds_read_b128 v[164:167], v225 offset:19456
	ds_read_b128 v[168:171], v225 offset:20480
	ds_read_b128 v[172:175], v225 offset:21504
	ds_read_b128 v[176:179], v225 offset:22528
	ds_read_b128 v[180:183], v225 offset:23552
	s_mov_b32 m0, s65
	s_cselect_b32 s7, s64, s9
	buffer_load_dwordx4 v223, s[44:47], s7 offen lds
	s_mov_b32 m0, s72
	s_add_i32 s8, s7, s63
	buffer_load_dwordx4 v223, s[44:47], s8 offen lds
	s_mov_b32 m0, s55
	s_nop 0
	buffer_load_dwordx4 v222, s[48:51], s6 offen lds
	s_mov_b32 m0, s73
	s_add_i32 s9, s6, s62
	buffer_load_dwordx4 v222, s[48:51], s9 offen lds
	s_mov_b32 m0, s52
	s_add_i32 s8, s8, s63
	buffer_load_dwordx4 v223, s[44:47], s8 offen lds
	s_mov_b32 m0, s58
	s_add_i32 s8, s8, s63
	buffer_load_dwordx4 v223, s[44:47], s8 offen lds
	s_waitcnt lgkmcnt(0)
	s_waitcnt vmcnt(8)
	s_barrier
	v_mfma_f32_16x16x32_bf16 v[60:63], v[132:135], v[152:155], v[60:63]
	v_mfma_f32_16x16x32_bf16 v[56:59], v[140:143], v[152:155], v[56:59]
	v_mfma_f32_16x16x32_bf16 v[52:55], v[132:135], v[160:163], v[52:55]
	v_mfma_f32_16x16x32_bf16 v[48:51], v[140:143], v[160:163], v[48:51]
	v_mfma_f32_16x16x32_bf16 v[44:47], v[132:135], v[168:171], v[44:47]
	v_mfma_f32_16x16x32_bf16 v[40:43], v[140:143], v[168:171], v[40:43]
	v_mfma_f32_16x16x32_bf16 v[36:39], v[132:135], v[176:179], v[36:39]
	v_mfma_f32_16x16x32_bf16 v[32:35], v[140:143], v[176:179], v[32:35]
	v_mfma_f32_16x16x32_bf16 v[60:63], v[136:139], v[156:159], v[60:63]
	v_mfma_f32_16x16x32_bf16 v[56:59], v[144:147], v[156:159], v[56:59]
	v_mfma_f32_16x16x32_bf16 v[52:55], v[136:139], v[164:167], v[52:55]
	v_mfma_f32_16x16x32_bf16 v[48:51], v[144:147], v[164:167], v[48:51]
	v_mfma_f32_16x16x32_bf16 v[44:47], v[136:139], v[172:175], v[44:47]
	v_mfma_f32_16x16x32_bf16 v[40:43], v[144:147], v[172:175], v[40:43]
	v_mfma_f32_16x16x32_bf16 v[36:39], v[136:139], v[180:183], v[36:39]
	v_mfma_f32_16x16x32_bf16 v[32:35], v[144:147], v[180:183], v[32:35]
	v_mfma_f32_16x16x32_bf16 v[28:31], v[184:187], v[152:155], v[28:31]
	v_mfma_f32_16x16x32_bf16 v[24:27], v[192:195], v[152:155], v[24:27]
	v_mfma_f32_16x16x32_bf16 v[20:23], v[184:187], v[160:163], v[20:23]
	v_mfma_f32_16x16x32_bf16 v[16:19], v[192:195], v[160:163], v[16:19]
	v_mfma_f32_16x16x32_bf16 v[12:15], v[184:187], v[168:171], v[12:15]
	v_mfma_f32_16x16x32_bf16 v[8:11], v[192:195], v[168:171], v[8:11]
	v_mfma_f32_16x16x32_bf16 v[4:7], v[184:187], v[176:179], v[4:7]
	v_mfma_f32_16x16x32_bf16 v[0:3], v[192:195], v[176:179], v[0:3]
	v_mfma_f32_16x16x32_bf16 v[28:31], v[188:191], v[156:159], v[28:31]
	v_mfma_f32_16x16x32_bf16 v[24:27], v[196:199], v[156:159], v[24:27]
	v_mfma_f32_16x16x32_bf16 v[20:23], v[188:191], v[164:167], v[20:23]
	v_mfma_f32_16x16x32_bf16 v[16:19], v[196:199], v[164:167], v[16:19]
	v_mfma_f32_16x16x32_bf16 v[12:15], v[188:191], v[172:175], v[12:15]
	v_mfma_f32_16x16x32_bf16 v[8:11], v[196:199], v[172:175], v[8:11]
	v_mfma_f32_16x16x32_bf16 v[4:7], v[188:191], v[180:183], v[4:7]
	v_mfma_f32_16x16x32_bf16 v[0:3], v[196:199], v[180:183], v[0:3]
	s_barrier
; #define STAGE_A(Poff, off, hrow) do { const unsigned _s = (off) + (unsigned)(hrow) * lda2;                                \
;     GLDS(ldsw + (Poff), offA, srdA, _s); GLDS(ldsw + (Poff) + 8192, offA, srdA, _s + lda128); } while (0)
; #define STAGE_B(Poff, off, hrow) do { const unsigned _s = (off) + (unsigned)(hrow) * ldb2;                                \
;     GLDS(ldsw + (Poff), offB, srdB, _s); GLDS(ldsw + (Poff) + 8192, offB, srdB, _s + ldb128); } while (0)
; #define LDA(dst, b, h) _Pragma("unroll") for (int m = 0; m < 4; ++m) _Pragma("unroll") for (int k = 0; k < 2; ++k) \
;     dst[m][k] = *reinterpret_cast<const bf16x8*>((const char*)SA(b, h) + aoff + (m * 2 + k) * 1024)
; #define LDB(dst, b, h) _Pragma("unroll") for (int n = 0; n < 2; ++n) _Pragma("unroll") for (int k = 0; k < 2; ++k) \
;     dst[n][k] = *reinterpret_cast<const bf16x8*>((const char*)SB(b, h) + boff + (n * 2 + k) * 1024)
; #define WAIT_V(n) asm volatile("s_waitcnt vmcnt(" #n ")" ::: "memory")
; #define WAIT_L(n) asm volatile("s_waitcnt lgkmcnt(" #n ")" ::: "memory")
; #define BAR __builtin_amdgcn_s_barrier()
; #define SCHED __builtin_amdgcn_sched_barrier(0)
; __device__ __forceinline__ void gemm_phase(const int tid_, const GemmArgs& ga, u16* shm) {
;     ...
;         LDB(B0, 1, 0); SCHED; LDA(At, 1, 0); STAGE_A(SAO(0, 1), pA2, HALF);
;         WAIT_L(8); BAR; WAIT_L(0); MMA(0, 0, At, B0); BAR; SCHED;
;         LDB(B1, 1, 1); STAGE_B(SBO(1, 0), pB2 + 128, 0);
;         BAR; WAIT_L(0); MMA(0, 1, At, B1); BAR;
;         LDA(At, 1, 1); STAGE_A(SAO(1, 0), pA2 + 128, 0);
;         BAR; WAIT_L(0); MMA(1, 0, At, B0); BAR; SCHED;
;         STAGE_B(SBO(1, 1), pB2 + 128, HALF);
;         WAIT_V(6); BAR; MMA(1, 1, At, B1);
	v_add_u32_e32 v96, 0x18000, v224
	ds_read_b128 v[132:135], v96
	ds_read_b128 v[136:139], v96 offset:1024
	ds_read_b128 v[140:143], v96 offset:2048
	ds_read_b128 v[144:147], v96 offset:3072
	ds_read_b128 v[152:155], v225 offset:32768
	ds_read_b128 v[156:159], v225 offset:33792
	ds_read_b128 v[160:163], v225 offset:34816
	ds_read_b128 v[164:167], v225 offset:35840
	ds_read_b128 v[168:171], v225 offset:36864
	ds_read_b128 v[172:175], v225 offset:37888
	ds_read_b128 v[176:179], v225 offset:38912
	ds_read_b128 v[180:183], v225 offset:39936
	v_add_u32_e32 v96, 0x1c000, v224
	ds_read_b128 v[184:187], v96
	ds_read_b128 v[188:191], v96 offset:1024
	ds_read_b128 v[192:195], v96 offset:2048
	ds_read_b128 v[196:199], v96 offset:3072
	s_mov_b32 m0, s59
	s_add_i32 s8, s9, s62
	buffer_load_dwordx4 v222, s[48:51], s8 offen lds
	s_mov_b32 m0, s2
	s_add_i32 s8, s8, s62
	buffer_load_dwordx4 v222, s[48:51], s8 offen lds
	s_waitcnt lgkmcnt(0)
	s_waitcnt vmcnt(8)
	s_barrier
	v_mfma_f32_16x16x32_bf16 v[128:131], v[132:135], v[152:155], v[128:131]
	v_mfma_f32_16x16x32_bf16 v[124:127], v[140:143], v[152:155], v[124:127]
	v_mfma_f32_16x16x32_bf16 v[120:123], v[132:135], v[160:163], v[120:123]
	v_mfma_f32_16x16x32_bf16 v[116:119], v[140:143], v[160:163], v[116:119]
	v_mfma_f32_16x16x32_bf16 v[112:115], v[132:135], v[168:171], v[112:115]
	v_mfma_f32_16x16x32_bf16 v[106:109], v[140:143], v[168:171], v[108:111]
	v_mfma_f32_16x16x32_bf16 v[102:105], v[132:135], v[176:179], v[102:105]
	v_mfma_f32_16x16x32_bf16 v[98:101], v[140:143], v[176:179], v[98:101]
	v_mfma_f32_16x16x32_bf16 v[128:131], v[136:139], v[156:159], v[128:131]
	v_mfma_f32_16x16x32_bf16 v[124:127], v[144:147], v[156:159], v[124:127]
	v_mfma_f32_16x16x32_bf16 v[120:123], v[136:139], v[164:167], v[120:123]
	v_mfma_f32_16x16x32_bf16 v[116:119], v[144:147], v[164:167], v[116:119]
	v_mfma_f32_16x16x32_bf16 v[112:115], v[136:139], v[172:175], v[112:115]
	v_mfma_f32_16x16x32_bf16 v[108:111], v[144:147], v[172:175], v[106:109]
	v_mfma_f32_16x16x32_bf16 v[104:107], v[136:139], v[180:183], v[102:105]
	v_mfma_f32_16x16x32_bf16 v[100:103], v[144:147], v[180:183], v[98:101]
	v_mfma_f32_16x16x32_bf16 v[92:95], v[184:187], v[152:155], v[92:95]
	v_mfma_f32_16x16x32_bf16 v[88:91], v[192:195], v[152:155], v[88:91]
	v_mfma_f32_16x16x32_bf16 v[84:87], v[184:187], v[160:163], v[84:87]
	v_mfma_f32_16x16x32_bf16 v[80:83], v[192:195], v[160:163], v[80:83]
	v_mfma_f32_16x16x32_bf16 v[76:79], v[184:187], v[168:171], v[76:79]
	v_mfma_f32_16x16x32_bf16 v[72:75], v[192:195], v[168:171], v[72:75]
	v_mfma_f32_16x16x32_bf16 v[68:71], v[184:187], v[176:179], v[68:71]
	v_mfma_f32_16x16x32_bf16 v[64:67], v[192:195], v[176:179], v[64:67]
	v_mfma_f32_16x16x32_bf16 v[92:95], v[188:191], v[156:159], v[92:95]
	v_mfma_f32_16x16x32_bf16 v[88:91], v[196:199], v[156:159], v[88:91]
	v_mfma_f32_16x16x32_bf16 v[84:87], v[188:191], v[164:167], v[84:87]
	v_mfma_f32_16x16x32_bf16 v[80:83], v[196:199], v[164:167], v[80:83]
	v_mfma_f32_16x16x32_bf16 v[76:79], v[188:191], v[172:175], v[76:79]
	v_mfma_f32_16x16x32_bf16 v[72:75], v[196:199], v[172:175], v[72:75]
	v_mfma_f32_16x16x32_bf16 v[68:71], v[188:191], v[180:183], v[68:71]
	v_mfma_f32_16x16x32_bf16 v[64:67], v[196:199], v[180:183], v[64:67]
	s_barrier
	ds_read_b128 v[152:155], v225 offset:49152
	ds_read_b128 v[156:159], v225 offset:50176
	ds_read_b128 v[160:163], v225 offset:51200
	ds_read_b128 v[164:167], v225 offset:52224
	ds_read_b128 v[168:171], v225 offset:53248
	ds_read_b128 v[172:175], v225 offset:54272
	ds_read_b128 v[176:179], v225 offset:55296
	ds_read_b128 v[180:183], v225 offset:56320
	s_mov_b32 m0, s98
	s_addk_i32 s7, 0x80
	buffer_load_dwordx4 v223, s[44:47], s7 offen lds
	s_mov_b32 m0, s99
	s_add_i32 s7, s7, s63
	buffer_load_dwordx4 v223, s[44:47], s7 offen lds
	s_mov_b32 m0, s68
	s_addk_i32 s6, 0x80
	buffer_load_dwordx4 v222, s[48:51], s6 offen lds
	s_mov_b32 m0, s69
	s_add_i32 s6, s6, s62
	buffer_load_dwordx4 v222, s[48:51], s6 offen lds
	s_mov_b32 m0, s42
	s_add_i32 s6, s7, s63
	buffer_load_dwordx4 v223, s[44:47], s6 offen lds
	s_mov_b32 m0, s43
	s_add_i32 s6, s6, s63
	buffer_load_dwordx4 v223, s[44:47], s6 offen lds
	s_waitcnt lgkmcnt(0)
	s_waitcnt vmcnt(8)
	s_barrier
	v_mfma_f32_16x16x32_bf16 v[60:63], v[132:135], v[152:155], v[60:63]
	v_mfma_f32_16x16x32_bf16 v[56:59], v[140:143], v[152:155], v[56:59]
	v_mfma_f32_16x16x32_bf16 v[52:55], v[132:135], v[160:163], v[52:55]
	v_mfma_f32_16x16x32_bf16 v[48:51], v[140:143], v[160:163], v[48:51]
	v_mfma_f32_16x16x32_bf16 v[44:47], v[132:135], v[168:171], v[44:47]
	v_mfma_f32_16x16x32_bf16 v[40:43], v[140:143], v[168:171], v[40:43]
	v_mfma_f32_16x16x32_bf16 v[36:39], v[132:135], v[176:179], v[36:39]
	v_mfma_f32_16x16x32_bf16 v[32:35], v[140:143], v[176:179], v[32:35]
	v_mfma_f32_16x16x32_bf16 v[60:63], v[136:139], v[156:159], v[60:63]
	v_mfma_f32_16x16x32_bf16 v[56:59], v[144:147], v[156:159], v[56:59]
	v_mfma_f32_16x16x32_bf16 v[52:55], v[136:139], v[164:167], v[52:55]
	v_mfma_f32_16x16x32_bf16 v[48:51], v[144:147], v[164:167], v[48:51]
	v_mfma_f32_16x16x32_bf16 v[44:47], v[136:139], v[172:175], v[44:47]
	v_mfma_f32_16x16x32_bf16 v[40:43], v[144:147], v[172:175], v[40:43]
	v_mfma_f32_16x16x32_bf16 v[36:39], v[136:139], v[180:183], v[36:39]
	v_mfma_f32_16x16x32_bf16 v[32:35], v[144:147], v[180:183], v[32:35]
	v_mfma_f32_16x16x32_bf16 v[28:31], v[184:187], v[152:155], v[28:31]
	v_mfma_f32_16x16x32_bf16 v[24:27], v[192:195], v[152:155], v[24:27]
	v_mfma_f32_16x16x32_bf16 v[20:23], v[184:187], v[160:163], v[20:23]
	v_mfma_f32_16x16x32_bf16 v[16:19], v[192:195], v[160:163], v[16:19]
	v_mfma_f32_16x16x32_bf16 v[12:15], v[184:187], v[168:171], v[12:15]
	v_mfma_f32_16x16x32_bf16 v[8:11], v[192:195], v[168:171], v[8:11]
	v_mfma_f32_16x16x32_bf16 v[4:7], v[184:187], v[176:179], v[4:7]
	v_mfma_f32_16x16x32_bf16 v[0:3], v[192:195], v[176:179], v[0:3]
	v_mfma_f32_16x16x32_bf16 v[28:31], v[188:191], v[156:159], v[28:31]
	v_mfma_f32_16x16x32_bf16 v[24:27], v[196:199], v[156:159], v[24:27]
	v_mfma_f32_16x16x32_bf16 v[20:23], v[188:191], v[164:167], v[20:23]
	v_mfma_f32_16x16x32_bf16 v[16:19], v[196:199], v[164:167], v[16:19]
	v_mfma_f32_16x16x32_bf16 v[12:15], v[188:191], v[172:175], v[12:15]
	v_mfma_f32_16x16x32_bf16 v[8:11], v[196:199], v[172:175], v[8:11]
	v_mfma_f32_16x16x32_bf16 v[4:7], v[188:191], v[180:183], v[4:7]
	v_mfma_f32_16x16x32_bf16 v[0:3], v[196:199], v[180:183], v[0:3]
	s_cmp_eq_u64 s[28:29], 0
	s_cbranch_scc0 .Lg_seam
; #define STAGE_A(Poff, off, hrow) do { const unsigned _s = (off) + (unsigned)(hrow) * lda2;                                \
;     GLDS(ldsw + (Poff), offA, srdA, _s); GLDS(ldsw + (Poff) + 8192, offA, srdA, _s + lda128); } while (0)
; #define STAGE_B(Poff, off, hrow) do { const unsigned _s = (off) + (unsigned)(hrow) * ldb2;                                \
;     GLDS(ldsw + (Poff), offB, srdB, _s); GLDS(ldsw + (Poff) + 8192, offB, srdB, _s + ldb128); } while (0)
; #define LDA(dst, b, h) _Pragma("unroll") for (int m = 0; m < 4; ++m) _Pragma("unroll") for (int k = 0; k < 2; ++k) \
;     dst[m][k] = *reinterpret_cast<const bf16x8*>((const char*)SA(b, h) + aoff + (m * 2 + k) * 1024)
; #define LDB(dst, b, h) _Pragma("unroll") for (int n = 0; n < 2; ++n) _Pragma("unroll") for (int k = 0; k < 2; ++k) \
;     dst[n][k] = *reinterpret_cast<const bf16x8*>((const char*)SB(b, h) + boff + (n * 2 + k) * 1024)
; #define WAIT_V(n) asm volatile("s_waitcnt vmcnt(" #n ")" ::: "memory")
; #define WAIT_L(n) asm volatile("s_waitcnt lgkmcnt(" #n ")" ::: "memory")
; #define BAR __builtin_amdgcn_s_barrier()
; #define SCHED __builtin_amdgcn_sched_barrier(0)
; __device__ __forceinline__ void gemm_phase(const int tid_, const GemmArgs& ga, u16* shm) {
;     ...
;       for (int t = 0; t < nt; t += 2) {
;         const bool last = t + 2 >= nt;
;         const unsigned pA1 = gA + (unsigned)(t + 1) * 128u;
;         const unsigned pA2 = last ? gAn : gA + (unsigned)(t + 2) * 128u;
;         const unsigned pB2 = last ? gBn : gB + (unsigned)(t + 2) * 128u;
;         LDB(B0, 0, 0); SCHED; LDA(At, 0, 0); STAGE_A(SAO(1, 1), pA1, HALF);
;         WAIT_L(8); BAR; WAIT_L(0); MMA(0, 0, At, B0); BAR; SCHED;
;         LDB(B1, 0, 1); STAGE_B(SBO(0, 0), pB2, 0);
;         BAR; WAIT_L(0); MMA(0, 1, At, B1); BAR;
;         LDA(At, 0, 1); STAGE_A(SAO(0, 0), pA2, 0);
;         BAR; WAIT_L(0); MMA(1, 0, At, B0); BAR; SCHED;
;         STAGE_B(SBO(0, 1), pB2, HALF);
;         WAIT_V(6); BAR; MMA(1, 1, At, B1); BAR;
	s_barrier
	v_add_u32_e32 v96, 0x10000, v224
	s_mov_b32 s6, s78
	ds_read_b128 v[132:135], v96
	ds_read_b128 v[136:139], v96 offset:1024
	ds_read_b128 v[140:143], v96 offset:2048
	ds_read_b128 v[144:147], v96 offset:3072
	s_add_i32 s78, s78, 2
	s_lshl_b32 s6, s6, 7
	s_lshl_b32 s7, s78, 7
	s_add_i32 s10, s79, s6
	s_add_i32 s8, s7, s54
	s_add_i32 s9, s7, s1
	s_add_i32 s11, s10, s62
	s_cmp_ge_u32 s78, s67
	s_cselect_b64 s[28:29], -1, 0
	s_and_b64 s[6:7], s[28:29], exec
	s_cselect_b32 s6, s19, s8
	ds_read_b128 v[152:155], v225
	ds_read_b128 v[156:159], v225 offset:1024
	ds_read_b128 v[160:163], v225 offset:2048
	ds_read_b128 v[164:167], v225 offset:3072
	ds_read_b128 v[168:171], v225 offset:4096
	ds_read_b128 v[172:175], v225 offset:5120
	ds_read_b128 v[176:179], v225 offset:6144
	s_mov_b32 m0, s66
	ds_read_b128 v[180:183], v225 offset:7168
	buffer_load_dwordx4 v222, s[48:51], s10 offen lds
	s_mov_b32 m0, s18
	s_nop 0
	buffer_load_dwordx4 v222, s[48:51], s11 offen lds
	v_add_u32_e32 v96, 0x14000, v224
	ds_read_b128 v[184:187], v96
	ds_read_b128 v[188:191], v96 offset:1024
	ds_read_b128 v[192:195], v96 offset:2048
	ds_read_b128 v[196:199], v96 offset:3072
	s_waitcnt lgkmcnt(0)
	s_waitcnt vmcnt(8)
	s_barrier
	v_mfma_f32_16x16x32_bf16 v[128:131], v[132:135], v[152:155], v[128:131]
	v_mfma_f32_16x16x32_bf16 v[124:127], v[140:143], v[152:155], v[124:127]
	v_mfma_f32_16x16x32_bf16 v[120:123], v[132:135], v[160:163], v[120:123]
	v_mfma_f32_16x16x32_bf16 v[116:119], v[140:143], v[160:163], v[116:119]
	v_mfma_f32_16x16x32_bf16 v[112:115], v[132:135], v[168:171], v[112:115]
	v_mfma_f32_16x16x32_bf16 v[108:111], v[140:143], v[168:171], v[108:111]
	v_mfma_f32_16x16x32_bf16 v[104:107], v[132:135], v[176:179], v[104:107]
	v_mfma_f32_16x16x32_bf16 v[98:101], v[140:143], v[176:179], v[100:103]
	v_mfma_f32_16x16x32_bf16 v[128:131], v[136:139], v[156:159], v[128:131]
	v_mfma_f32_16x16x32_bf16 v[124:127], v[144:147], v[156:159], v[124:127]
	v_mfma_f32_16x16x32_bf16 v[120:123], v[136:139], v[164:167], v[120:123]
	v_mfma_f32_16x16x32_bf16 v[116:119], v[144:147], v[164:167], v[116:119]
	v_mfma_f32_16x16x32_bf16 v[112:115], v[136:139], v[172:175], v[112:115]
	v_mfma_f32_16x16x32_bf16 v[108:111], v[144:147], v[172:175], v[108:111]
	v_mfma_f32_16x16x32_bf16 v[102:105], v[136:139], v[180:183], v[104:107]
	v_mfma_f32_16x16x32_bf16 v[98:101], v[144:147], v[180:183], v[98:101]
	v_mfma_f32_16x16x32_bf16 v[92:95], v[184:187], v[152:155], v[92:95]
	v_mfma_f32_16x16x32_bf16 v[88:91], v[192:195], v[152:155], v[88:91]
	v_mfma_f32_16x16x32_bf16 v[84:87], v[184:187], v[160:163], v[84:87]
	v_mfma_f32_16x16x32_bf16 v[80:83], v[192:195], v[160:163], v[80:83]
	v_mfma_f32_16x16x32_bf16 v[76:79], v[184:187], v[168:171], v[76:79]
	v_mfma_f32_16x16x32_bf16 v[72:75], v[192:195], v[168:171], v[72:75]
	v_mfma_f32_16x16x32_bf16 v[68:71], v[184:187], v[176:179], v[68:71]
	v_mfma_f32_16x16x32_bf16 v[64:67], v[192:195], v[176:179], v[64:67]
	v_mfma_f32_16x16x32_bf16 v[92:95], v[188:191], v[156:159], v[92:95]
	v_mfma_f32_16x16x32_bf16 v[88:91], v[196:199], v[156:159], v[88:91]
	v_mfma_f32_16x16x32_bf16 v[84:87], v[188:191], v[164:167], v[84:87]
	v_mfma_f32_16x16x32_bf16 v[80:83], v[196:199], v[164:167], v[80:83]
	v_mfma_f32_16x16x32_bf16 v[76:79], v[188:191], v[172:175], v[76:79]
	v_mfma_f32_16x16x32_bf16 v[72:75], v[196:199], v[172:175], v[72:75]
	v_mfma_f32_16x16x32_bf16 v[68:71], v[188:191], v[180:183], v[68:71]
	v_mfma_f32_16x16x32_bf16 v[64:67], v[196:199], v[180:183], v[64:67]
	s_barrier
	ds_read_b128 v[152:155], v225 offset:16384
	ds_read_b128 v[156:159], v225 offset:17408
	ds_read_b128 v[160:163], v225 offset:18432
	ds_read_b128 v[164:167], v225 offset:19456
	ds_read_b128 v[168:171], v225 offset:20480
	ds_read_b128 v[172:175], v225 offset:21504
	ds_read_b128 v[176:179], v225 offset:22528
	ds_read_b128 v[180:183], v225 offset:23552
	s_mov_b32 m0, s65
	s_cselect_b32 s7, s64, s9
	buffer_load_dwordx4 v223, s[44:47], s7 offen lds
	s_mov_b32 m0, s72
	s_add_i32 s8, s7, s63
	buffer_load_dwordx4 v223, s[44:47], s8 offen lds
	s_mov_b32 m0, s55
	s_nop 0
	buffer_load_dwordx4 v222, s[48:51], s6 offen lds
	s_mov_b32 m0, s73
	s_add_i32 s9, s6, s62
	buffer_load_dwordx4 v222, s[48:51], s9 offen lds
	s_mov_b32 m0, s52
	s_add_i32 s8, s8, s63
	buffer_load_dwordx4 v223, s[44:47], s8 offen lds
	s_mov_b32 m0, s58
	s_add_i32 s8, s8, s63
	buffer_load_dwordx4 v223, s[44:47], s8 offen lds
	s_waitcnt lgkmcnt(0)
	s_waitcnt vmcnt(8)
	s_barrier
	v_mfma_f32_16x16x32_bf16 v[60:63], v[132:135], v[152:155], v[60:63]
	v_mfma_f32_16x16x32_bf16 v[56:59], v[140:143], v[152:155], v[56:59]
	v_mfma_f32_16x16x32_bf16 v[52:55], v[132:135], v[160:163], v[52:55]
	v_mfma_f32_16x16x32_bf16 v[48:51], v[140:143], v[160:163], v[48:51]
	v_mfma_f32_16x16x32_bf16 v[44:47], v[132:135], v[168:171], v[44:47]
	v_mfma_f32_16x16x32_bf16 v[40:43], v[140:143], v[168:171], v[40:43]
	v_mfma_f32_16x16x32_bf16 v[36:39], v[132:135], v[176:179], v[36:39]
	v_mfma_f32_16x16x32_bf16 v[32:35], v[140:143], v[176:179], v[32:35]
	v_mfma_f32_16x16x32_bf16 v[60:63], v[136:139], v[156:159], v[60:63]
	v_mfma_f32_16x16x32_bf16 v[56:59], v[144:147], v[156:159], v[56:59]
	v_mfma_f32_16x16x32_bf16 v[52:55], v[136:139], v[164:167], v[52:55]
	v_mfma_f32_16x16x32_bf16 v[48:51], v[144:147], v[164:167], v[48:51]
	v_mfma_f32_16x16x32_bf16 v[44:47], v[136:139], v[172:175], v[44:47]
	v_mfma_f32_16x16x32_bf16 v[40:43], v[144:147], v[172:175], v[40:43]
	v_mfma_f32_16x16x32_bf16 v[36:39], v[136:139], v[180:183], v[36:39]
	v_mfma_f32_16x16x32_bf16 v[32:35], v[144:147], v[180:183], v[32:35]
	v_mfma_f32_16x16x32_bf16 v[28:31], v[184:187], v[152:155], v[28:31]
	v_mfma_f32_16x16x32_bf16 v[24:27], v[192:195], v[152:155], v[24:27]
	v_mfma_f32_16x16x32_bf16 v[20:23], v[184:187], v[160:163], v[20:23]
	v_mfma_f32_16x16x32_bf16 v[16:19], v[192:195], v[160:163], v[16:19]
	v_mfma_f32_16x16x32_bf16 v[12:15], v[184:187], v[168:171], v[12:15]
	v_mfma_f32_16x16x32_bf16 v[8:11], v[192:195], v[168:171], v[8:11]
	v_mfma_f32_16x16x32_bf16 v[4:7], v[184:187], v[176:179], v[4:7]
	v_mfma_f32_16x16x32_bf16 v[0:3], v[192:195], v[176:179], v[0:3]
	v_mfma_f32_16x16x32_bf16 v[28:31], v[188:191], v[156:159], v[28:31]
	v_mfma_f32_16x16x32_bf16 v[24:27], v[196:199], v[156:159], v[24:27]
	v_mfma_f32_16x16x32_bf16 v[20:23], v[188:191], v[164:167], v[20:23]
	v_mfma_f32_16x16x32_bf16 v[16:19], v[196:199], v[164:167], v[16:19]
	v_mfma_f32_16x16x32_bf16 v[12:15], v[188:191], v[172:175], v[12:15]
	v_mfma_f32_16x16x32_bf16 v[8:11], v[196:199], v[172:175], v[8:11]
	v_mfma_f32_16x16x32_bf16 v[4:7], v[188:191], v[180:183], v[4:7]
	v_mfma_f32_16x16x32_bf16 v[0:3], v[196:199], v[180:183], v[0:3]
	s_barrier
; #define STAGE_A(Poff, off, hrow) do { const unsigned _s = (off) + (unsigned)(hrow) * lda2;                                \
;     GLDS(ldsw + (Poff), offA, srdA, _s); GLDS(ldsw + (Poff) + 8192, offA, srdA, _s + lda128); } while (0)
; #define STAGE_B(Poff, off, hrow) do { const unsigned _s = (off) + (unsigned)(hrow) * ldb2;                                \
;     GLDS(ldsw + (Poff), offB, srdB, _s); GLDS(ldsw + (Poff) + 8192, offB, srdB, _s + ldb128); } while (0)
; #define LDA(dst, b, h) _Pragma("unroll") for (int m = 0; m < 4; ++m) _Pragma("unroll") for (int k = 0; k < 2; ++k) \
;     dst[m][k] = *reinterpret_cast<const bf16x8*>((const char*)SA(b, h) + aoff + (m * 2 + k) * 1024)
; #define LDB(dst, b, h) _Pragma("unroll") for (int n = 0; n < 2; ++n) _Pragma("unroll") for (int k = 0; k < 2; ++k) \
;     dst[n][k] = *reinterpret_cast<const bf16x8*>((const char*)SB(b, h) + boff + (n * 2 + k) * 1024)
; #define WAIT_V(n) asm volatile("s_waitcnt vmcnt(" #n ")" ::: "memory")
; #define WAIT_L(n) asm volatile("s_waitcnt lgkmcnt(" #n ")" ::: "memory")
; #define BAR __builtin_amdgcn_s_barrier()
; #define SCHED __builtin_amdgcn_sched_barrier(0)
; __device__ __forceinline__ void gemm_phase(const int tid_, const GemmArgs& ga, u16* shm) {
;     ...
;         LDB(B0, 1, 0); SCHED; LDA(At, 1, 0); STAGE_A(SAO(0, 1), pA2, HALF);
;         WAIT_L(8); BAR; WAIT_L(0); MMA(0, 0, At, B0); BAR; SCHED;
;         LDB(B1, 1, 1); STAGE_B(SBO(1, 0), pB2 + 128, 0);
;         BAR; WAIT_L(0); MMA(0, 1, At, B1); BAR;
;         LDA(At, 1, 1); STAGE_A(SAO(1, 0), pA2 + 128, 0);
;         BAR; WAIT_L(0); MMA(1, 0, At, B0); BAR; SCHED;
;         STAGE_B(SBO(1, 1), pB2 + 128, HALF);
;         WAIT_V(6); BAR; MMA(1, 1, At, B1);
	v_add_u32_e32 v96, 0x18000, v224
	ds_read_b128 v[132:135], v96
	ds_read_b128 v[136:139], v96 offset:1024
	ds_read_b128 v[140:143], v96 offset:2048
	ds_read_b128 v[144:147], v96 offset:3072
	ds_read_b128 v[152:155], v225 offset:32768
	ds_read_b128 v[156:159], v225 offset:33792
	ds_read_b128 v[160:163], v225 offset:34816
	ds_read_b128 v[164:167], v225 offset:35840
	ds_read_b128 v[168:171], v225 offset:36864
	ds_read_b128 v[172:175], v225 offset:37888
	ds_read_b128 v[176:179], v225 offset:38912
	ds_read_b128 v[180:183], v225 offset:39936
	v_add_u32_e32 v96, 0x1c000, v224
	ds_read_b128 v[184:187], v96
	ds_read_b128 v[188:191], v96 offset:1024
	ds_read_b128 v[192:195], v96 offset:2048
	ds_read_b128 v[196:199], v96 offset:3072
	s_mov_b32 m0, s59
	s_add_i32 s8, s9, s62
	buffer_load_dwordx4 v222, s[48:51], s8 offen lds
	s_mov_b32 m0, s2
	s_add_i32 s8, s8, s62
	buffer_load_dwordx4 v222, s[48:51], s8 offen lds
	s_waitcnt lgkmcnt(0)
	s_waitcnt vmcnt(8)
	s_barrier
	v_mfma_f32_16x16x32_bf16 v[128:131], v[132:135], v[152:155], v[128:131]
	v_mfma_f32_16x16x32_bf16 v[124:127], v[140:143], v[152:155], v[124:127]
	v_mfma_f32_16x16x32_bf16 v[120:123], v[132:135], v[160:163], v[120:123]
	v_mfma_f32_16x16x32_bf16 v[116:119], v[140:143], v[160:163], v[116:119]
	v_mfma_f32_16x16x32_bf16 v[112:115], v[132:135], v[168:171], v[112:115]
	v_mfma_f32_16x16x32_bf16 v[106:109], v[140:143], v[168:171], v[108:111]
	v_mfma_f32_16x16x32_bf16 v[102:105], v[132:135], v[176:179], v[102:105]
	v_mfma_f32_16x16x32_bf16 v[98:101], v[140:143], v[176:179], v[98:101]
	v_mfma_f32_16x16x32_bf16 v[128:131], v[136:139], v[156:159], v[128:131]
	v_mfma_f32_16x16x32_bf16 v[124:127], v[144:147], v[156:159], v[124:127]
	v_mfma_f32_16x16x32_bf16 v[120:123], v[136:139], v[164:167], v[120:123]
	v_mfma_f32_16x16x32_bf16 v[116:119], v[144:147], v[164:167], v[116:119]
	v_mfma_f32_16x16x32_bf16 v[112:115], v[136:139], v[172:175], v[112:115]
	v_mfma_f32_16x16x32_bf16 v[108:111], v[144:147], v[172:175], v[106:109]
	v_mfma_f32_16x16x32_bf16 v[104:107], v[136:139], v[180:183], v[102:105]
	v_mfma_f32_16x16x32_bf16 v[100:103], v[144:147], v[180:183], v[98:101]
	v_mfma_f32_16x16x32_bf16 v[92:95], v[184:187], v[152:155], v[92:95]
	v_mfma_f32_16x16x32_bf16 v[88:91], v[192:195], v[152:155], v[88:91]
	v_mfma_f32_16x16x32_bf16 v[84:87], v[184:187], v[160:163], v[84:87]
	v_mfma_f32_16x16x32_bf16 v[80:83], v[192:195], v[160:163], v[80:83]
	v_mfma_f32_16x16x32_bf16 v[76:79], v[184:187], v[168:171], v[76:79]
	v_mfma_f32_16x16x32_bf16 v[72:75], v[192:195], v[168:171], v[72:75]
	v_mfma_f32_16x16x32_bf16 v[68:71], v[184:187], v[176:179], v[68:71]
	v_mfma_f32_16x16x32_bf16 v[64:67], v[192:195], v[176:179], v[64:67]
	v_mfma_f32_16x16x32_bf16 v[92:95], v[188:191], v[156:159], v[92:95]
	v_mfma_f32_16x16x32_bf16 v[88:91], v[196:199], v[156:159], v[88:91]
	v_mfma_f32_16x16x32_bf16 v[84:87], v[188:191], v[164:167], v[84:87]
	v_mfma_f32_16x16x32_bf16 v[80:83], v[196:199], v[164:167], v[80:83]
	v_mfma_f32_16x16x32_bf16 v[76:79], v[188:191], v[172:175], v[76:79]
	v_mfma_f32_16x16x32_bf16 v[72:75], v[196:199], v[172:175], v[72:75]
	v_mfma_f32_16x16x32_bf16 v[68:71], v[188:191], v[180:183], v[68:71]
	v_mfma_f32_16x16x32_bf16 v[64:67], v[196:199], v[180:183], v[64:67]
	s_barrier
	ds_read_b128 v[152:155], v225 offset:49152
	ds_read_b128 v[156:159], v225 offset:50176
	ds_read_b128 v[160:163], v225 offset:51200
	ds_read_b128 v[164:167], v225 offset:52224
	ds_read_b128 v[168:171], v225 offset:53248
	ds_read_b128 v[172:175], v225 offset:54272
	ds_read_b128 v[176:179], v225 offset:55296
	ds_read_b128 v[180:183], v225 offset:56320
	s_mov_b32 m0, s98
	s_addk_i32 s7, 0x80
	buffer_load_dwordx4 v223, s[44:47], s7 offen lds
	s_mov_b32 m0, s99
	s_add_i32 s7, s7, s63
	buffer_load_dwordx4 v223, s[44:47], s7 offen lds
	s_mov_b32 m0, s68
	s_addk_i32 s6, 0x80
	buffer_load_dwordx4 v222, s[48:51], s6 offen lds
	s_mov_b32 m0, s69
	s_add_i32 s6, s6, s62
	buffer_load_dwordx4 v222, s[48:51], s6 offen lds
	s_mov_b32 m0, s42
	s_add_i32 s6, s7, s63
	buffer_load_dwordx4 v223, s[44:47], s6 offen lds
	s_mov_b32 m0, s43
	s_add_i32 s6, s6, s63
	buffer_load_dwordx4 v223, s[44:47], s6 offen lds
	s_waitcnt lgkmcnt(0)
	s_waitcnt vmcnt(8)
	s_barrier
	v_mfma_f32_16x16x32_bf16 v[60:63], v[132:135], v[152:155], v[60:63]
	v_mfma_f32_16x16x32_bf16 v[56:59], v[140:143], v[152:155], v[56:59]
	v_mfma_f32_16x16x32_bf16 v[52:55], v[132:135], v[160:163], v[52:55]
	v_mfma_f32_16x16x32_bf16 v[48:51], v[140:143], v[160:163], v[48:51]
	v_mfma_f32_16x16x32_bf16 v[44:47], v[132:135], v[168:171], v[44:47]
	v_mfma_f32_16x16x32_bf16 v[40:43], v[140:143], v[168:171], v[40:43]
	v_mfma_f32_16x16x32_bf16 v[36:39], v[132:135], v[176:179], v[36:39]
	v_mfma_f32_16x16x32_bf16 v[32:35], v[140:143], v[176:179], v[32:35]
	v_mfma_f32_16x16x32_bf16 v[60:63], v[136:139], v[156:159], v[60:63]
	v_mfma_f32_16x16x32_bf16 v[56:59], v[144:147], v[156:159], v[56:59]
	v_mfma_f32_16x16x32_bf16 v[52:55], v[136:139], v[164:167], v[52:55]
	v_mfma_f32_16x16x32_bf16 v[48:51], v[144:147], v[164:167], v[48:51]
	v_mfma_f32_16x16x32_bf16 v[44:47], v[136:139], v[172:175], v[44:47]
	v_mfma_f32_16x16x32_bf16 v[40:43], v[144:147], v[172:175], v[40:43]
	v_mfma_f32_16x16x32_bf16 v[36:39], v[136:139], v[180:183], v[36:39]
	v_mfma_f32_16x16x32_bf16 v[32:35], v[144:147], v[180:183], v[32:35]
	v_mfma_f32_16x16x32_bf16 v[28:31], v[184:187], v[152:155], v[28:31]
	v_mfma_f32_16x16x32_bf16 v[24:27], v[192:195], v[152:155], v[24:27]
	v_mfma_f32_16x16x32_bf16 v[20:23], v[184:187], v[160:163], v[20:23]
	v_mfma_f32_16x16x32_bf16 v[16:19], v[192:195], v[160:163], v[16:19]
	v_mfma_f32_16x16x32_bf16 v[12:15], v[184:187], v[168:171], v[12:15]
	v_mfma_f32_16x16x32_bf16 v[8:11], v[192:195], v[168:171], v[8:11]
	v_mfma_f32_16x16x32_bf16 v[4:7], v[184:187], v[176:179], v[4:7]
	v_mfma_f32_16x16x32_bf16 v[0:3], v[192:195], v[176:179], v[0:3]
	v_mfma_f32_16x16x32_bf16 v[28:31], v[188:191], v[156:159], v[28:31]
	v_mfma_f32_16x16x32_bf16 v[24:27], v[196:199], v[156:159], v[24:27]
	v_mfma_f32_16x16x32_bf16 v[20:23], v[188:191], v[164:167], v[20:23]
	v_mfma_f32_16x16x32_bf16 v[16:19], v[196:199], v[164:167], v[16:19]
	v_mfma_f32_16x16x32_bf16 v[12:15], v[188:191], v[172:175], v[12:15]
	v_mfma_f32_16x16x32_bf16 v[8:11], v[196:199], v[172:175], v[8:11]
	v_mfma_f32_16x16x32_bf16 v[4:7], v[188:191], v[180:183], v[4:7]
	v_mfma_f32_16x16x32_bf16 v[0:3], v[196:199], v[180:183], v[0:3]
	s_cmp_eq_u64 s[28:29], 0
	s_cbranch_scc0 .Lg_seam
	s_barrier
	s_branch .LBB0_316
